# younger wave half (waves 4-7) runs its attention step blocks at s_setprio 2 (older half 1) to balance barrier arrival under the half-step stagger
# speedup vs baseline: 1.0452x; 1.0138x over previous
; #define LAS __attribute__((address_space(3)))
; DI unsigned cvt_pk(float lo, float hi) { unsigned r; asm volatile("v_cvt_pk_bf16_f32 %0, %1, %2" : "=v"(r) : "v"(lo), "v"(hi)); return r; }
; DI float fexp2(float x) { return __builtin_amdgcn_exp2f(x); }
; template <int DK, int DV, int MODE> ...
;     ...
;   auto part2 = [&](f32x16 (&st)[2], int t) __attribute__((always_inline)) {
;     float ps0 = 0.f, ps1 = 0.f, ps2 = 0.f, ps3 = 0.f;
; #pragma unroll
;     for (int kb = 0; kb < 2; ++kb)
; #pragma unroll
;       for (int i = 0; i < 16; i += 4) {
;         const float p0 = fexp2(st[kb][i]), p1 = fexp2(st[kb][i + 1]), p2 = fexp2(st[kb][i + 2]), p3 = fexp2(st[kb][i + 3]);
;         st[kb][i] = p0; st[kb][i + 1] = p1; st[kb][i + 2] = p2; st[kb][i + 3] = p3; ps0 += p0; ps1 += p1; ps2 += p2; ps3 += p3;
;       }
;     lsum += (ps0 + ps1) + (ps2 + ps3);
;     bf16x8 pf[2][2];
; #pragma unroll
;     for (int kb = 0; kb < 2; ++kb)
; #pragma unroll
;       for (int s = 0; s < 2; ++s) { u32x4 pp; pp.x = cvt_pk(st[kb][8 * s], st[kb][8 * s + 1]); pp.y = cvt_pk(st[kb][8 * s + 2], st[kb][8 * s + 3]); pp.z = cvt_pk(st[kb][8 * s + 4], st[kb][8 * s + 5]); pp.w = cvt_pk(st[kb][8 * s + 6], st[kb][8 * s + 7]); pf[kb][s] = __builtin_bit_cast(bf16x8, pp); }
; #pragma unroll
;     for (int db = 0; db < DV / 32; ++db)
; #pragma unroll
;       for (int kb = 0; kb < 2; ++kb)
; #pragma unroll
;         for (int s = 0; s < 2; ++s) {
;           if (MODE == 1 && ((kb == 1 && s == 1 && cwu == 0) || (kb == 0 && s == 0 && cwu != 0))) continue;
;           const bf16x8 vf = *(const LAS bf16x8*)(lds + ATT_VB + (t & 3) * VBUF + (32 * db + r) * VSTR + (2 * kb + s) * 32 + hh * 16);
;           O[db] = __builtin_amdgcn_mfma_f32_32x32x16_bf16(vf, pf[kb][s], O[db], 0, 0, 0);
;         }
;   };
.LBB0_134:
	s_setprio 1
	s_cmp_eq_u32 s32, 0
	s_cbranch_scc1 .Lstg_pre5
	s_waitcnt lgkmcnt(0)
	s_barrier
	s_setprio 2
.Lstg_pre5:
	s_add_i32 s73, s68, -4
	s_and_b32 s70, s73, 3
	s_mul_i32 s50, s70, 0x2400
	v_add_u32_e32 v3, s50, v235
	s_and_b32 s72, s72, 2
	s_mul_i32 s50, s72, 0x4800
	v_add_u32_e32 v224, s50, v237
	v_add_u32_e32 v224, 0xd000, v224
	ds_read_b128 v[4:7], v3
	ds_read_b128 v[8:11], v3 offset:32
	ds_read_b128 v[12:15], v3 offset:64
	ds_read_b128 v[196:199], v3 offset:96
	ds_read_b128 v[200:203], v3 offset:4608
	v_add_u32_e32 v0, 64, v242
	v_cmp_gt_i32_e64 s[50:51], s78, v0
	v_cmp_lt_i32_e32 vcc, s77, v0
	v_exp_f32_e32 v96, v96
	v_exp_f32_e32 v97, v97
	v_cndmask_b32_e64 v0, 0, v233, s[50:51]
	v_exp_f32_e32 v98, v98
	v_cndmask_b32_e32 v0, v0, v234, vcc
	v_cmp_neq_f32_e32 vcc, s53, v193
	v_exp_f32_e32 v99, v99
	v_exp_f32_e32 v100, v100
	v_exp_f32_e32 v101, v101
	v_cndmask_b32_e32 v2, 0, v193, vcc
	v_sub_f32_e32 v112, v0, v2
	v_mov_b32_e32 v113, v112
	v_mov_b32_e32 v114, v112
	v_mov_b32_e32 v115, v112
	v_mov_b32_e32 v116, v112
	v_mov_b32_e32 v117, v112
	v_mov_b32_e32 v118, v112
	v_mov_b32_e32 v119, v112
	v_mov_b32_e32 v120, v112
	v_mov_b32_e32 v121, v112
	v_mov_b32_e32 v122, v112
	v_mov_b32_e32 v123, v112
	v_mov_b32_e32 v124, v112
	v_mov_b32_e32 v125, v112
	v_mov_b32_e32 v126, v112
	v_mov_b32_e32 v127, v112
	v_exp_f32_e32 v102, v102
	v_exp_f32_e32 v103, v103
	s_waitcnt lgkmcnt(4)
	v_mfma_f32_32x32x16_bf16 v[128:143], v[4:7], v[144:147], v[112:127]
	ds_read_b128 v[4:7], v3 offset:4640
	v_add_f32_e32 v244, v96, v100
	v_add_f32_e32 v245, v97, v101
	v_add_f32_e32 v246, v98, v102
	v_add_f32_e32 v247, v99, v103
	v_cvt_pk_bf16_f32 v96, v96, v97
	v_cvt_pk_bf16_f32 v97, v98, v99
	v_cvt_pk_bf16_f32 v98, v100, v101
	s_waitcnt lgkmcnt(4)
	v_mfma_f32_32x32x16_bf16 v[128:143], v[8:11], v[148:151], v[128:143]
	ds_read_b128 v[8:11], v3 offset:4672
	v_cvt_pk_bf16_f32 v99, v102, v103
	v_exp_f32_e32 v104, v104
	v_exp_f32_e32 v105, v105
	v_exp_f32_e32 v106, v106
	s_waitcnt lgkmcnt(4)
	v_mfma_f32_32x32x16_bf16 v[128:143], v[12:15], v[152:155], v[128:143]
	ds_read_b128 v[12:15], v3 offset:4704
	v_exp_f32_e32 v107, v107
	v_exp_f32_e32 v108, v108
	v_exp_f32_e32 v109, v109
	v_exp_f32_e32 v110, v110
	s_waitcnt lgkmcnt(4)
	v_mfma_f32_32x32x16_bf16 v[128:143], v[196:199], v[156:159], v[128:143]
	ds_read_b128 v[196:199], v224
	v_exp_f32_e32 v111, v111
	v_add_f32_e32 v244, v104, v244
	v_add_f32_e32 v245, v105, v245
	v_add_f32_e32 v246, v106, v246
	v_add_f32_e32 v247, v107, v247
	v_add_f32_e32 v244, v108, v244
	s_waitcnt lgkmcnt(4)
	v_mfma_f32_32x32x16_bf16 v[112:127], v[200:203], v[144:147], v[112:127]
	ds_read_b128 v[200:203], v224 offset:4608
	v_add_f32_e32 v245, v109, v245
	v_add_f32_e32 v246, v110, v246
	v_add_f32_e32 v247, v111, v247
	v_cvt_pk_bf16_f32 v104, v104, v105
	v_cvt_pk_bf16_f32 v105, v106, v107
	v_cvt_pk_bf16_f32 v106, v108, v109
	v_cvt_pk_bf16_f32 v107, v110, v111
	s_waitcnt lgkmcnt(4)
	v_mfma_f32_32x32x16_bf16 v[112:127], v[4:7], v[148:151], v[112:127]
	ds_read_b128 v[4:7], v224 offset:9216
	v_exp_f32_e32 v80, v80
	v_exp_f32_e32 v81, v81
	v_exp_f32_e32 v82, v82
	v_exp_f32_e32 v83, v83
	s_waitcnt lgkmcnt(4)
	v_mfma_f32_32x32x16_bf16 v[112:127], v[8:11], v[152:155], v[112:127]
	ds_read_b128 v[8:11], v224 offset:13824
	v_exp_f32_e32 v84, v84
	v_exp_f32_e32 v85, v85
	v_exp_f32_e32 v86, v86
	v_exp_f32_e32 v87, v87
	s_waitcnt lgkmcnt(4)
	v_mfma_f32_32x32x16_bf16 v[112:127], v[12:15], v[156:159], v[112:127]
	ds_read_b128 v[12:15], v224 offset:32
	v_add_f32_e32 v244, v80, v244
	v_add_f32_e32 v245, v81, v245
	v_add_f32_e32 v246, v82, v246
	v_add_f32_e32 v247, v83, v247
	v_add_f32_e32 v244, v84, v244
	v_add_f32_e32 v245, v85, v245
	v_add_f32_e32 v246, v86, v246
	s_waitcnt lgkmcnt(4)
; #define LAS __attribute__((address_space(3)))
; template <int DK, int DV, int MODE> ...
;     ...
;     float mx = fmaxf(st[0][0], st[1][0]);
; #pragma unroll
;     for (int i = 1; i < 16; ++i) mx = fmaxf(fmaxf(mx, st[0][i]), st[1][i]);
;     mx = fmaxf(mx, __shfl_xor(mx, 32));
;     ...
; #pragma unroll
;     for (int db = 0; db < DV / 32; ++db)
; #pragma unroll
;       for (int kb = 0; kb < 2; ++kb)
; #pragma unroll
;         for (int s = 0; s < 2; ++s) {
;           if (MODE == 1 && ((kb == 1 && s == 1 && cwu == 0) || (kb == 0 && s == 0 && cwu != 0))) continue;
;           const bf16x8 vf = *(const LAS bf16x8*)(lds + ATT_VB + (t & 3) * VBUF + (32 * db + r) * VSTR + (2 * kb + s) * 32 + hh * 16);
;           O[db] = __builtin_amdgcn_mfma_f32_32x32x16_bf16(vf, pf[kb][s], O[db], 0, 0, 0);
;         }
;   };
	v_mfma_f32_32x32x16_bf16 v[64:79], v[196:199], v[96:99], v[64:79]
	ds_read_b128 v[196:199], v224 offset:4640
	v_add_f32_e32 v247, v87, v247
	v_cvt_pk_bf16_f32 v80, v80, v81
	v_cvt_pk_bf16_f32 v81, v82, v83
	v_cvt_pk_bf16_f32 v82, v84, v85
	v_cvt_pk_bf16_f32 v83, v86, v87
	v_exp_f32_e32 v88, v88
	s_waitcnt lgkmcnt(4)
	v_mfma_f32_32x32x16_bf16 v[48:63], v[200:203], v[96:99], v[48:63]
	ds_read_b128 v[200:203], v224 offset:9248
	v_exp_f32_e32 v89, v89
	v_exp_f32_e32 v90, v90
	v_exp_f32_e32 v91, v91
	v_exp_f32_e32 v92, v92
	s_waitcnt lgkmcnt(4)
	v_mfma_f32_32x32x16_bf16 v[32:47], v[4:7], v[96:99], v[32:47]
	ds_read_b128 v[4:7], v224 offset:13856
	v_exp_f32_e32 v93, v93
	v_exp_f32_e32 v94, v94
	v_exp_f32_e32 v95, v95
	v_add_f32_e32 v244, v88, v244
	s_waitcnt lgkmcnt(4)
	v_mfma_f32_32x32x16_bf16 v[16:31], v[8:11], v[96:99], v[16:31]
	ds_read_b128 v[8:11], v224 offset:64
	v_add_f32_e32 v245, v89, v245
	v_add_f32_e32 v246, v90, v246
	v_add_f32_e32 v247, v91, v247
	v_add_f32_e32 v244, v92, v244
	v_add_f32_e32 v245, v93, v245
	v_add_f32_e32 v246, v94, v246
	v_add_f32_e32 v247, v95, v247
	s_waitcnt lgkmcnt(4)
	v_mfma_f32_32x32x16_bf16 v[64:79], v[12:15], v[104:107], v[64:79]
	ds_read_b128 v[12:15], v224 offset:4672
	v_cvt_pk_bf16_f32 v88, v88, v89
	v_cvt_pk_bf16_f32 v89, v90, v91
	v_cvt_pk_bf16_f32 v90, v92, v93
	v_cvt_pk_bf16_f32 v91, v94, v95
	v_add_f32_e32 v244, v244, v245
	v_add_f32_e32 v246, v246, v247
	v_max3_f32 v248, v128, v129, v130
	s_waitcnt lgkmcnt(4)
	v_mfma_f32_32x32x16_bf16 v[48:63], v[196:199], v[104:107], v[48:63]
	ds_read_b128 v[196:199], v224 offset:9280
	v_max3_f32 v249, v135, v136, v137
	v_max3_f32 v248, v248, v131, v132
	v_max3_f32 v249, v249, v138, v139
	v_max3_f32 v248, v248, v133, v134
	v_max3_f32 v249, v249, v140, v141
	v_max3_f32 v250, v112, v113, v114
	v_max3_f32 v251, v119, v120, v121
	s_waitcnt lgkmcnt(4)
	v_mfma_f32_32x32x16_bf16 v[32:47], v[200:203], v[104:107], v[32:47]
	ds_read_b128 v[200:203], v224 offset:13888
	v_max3_f32 v250, v250, v115, v116
	v_max3_f32 v251, v251, v122, v123
	v_max3_f32 v250, v250, v117, v118
	v_max3_f32 v251, v251, v124, v125
	v_max3_f32 v248, v248, v249, v142
	v_max3_f32 v250, v250, v251, v126
	v_max3_f32 v248, v248, v143, v127
	s_waitcnt lgkmcnt(4)
	v_mfma_f32_32x32x16_bf16 v[16:31], v[4:7], v[104:107], v[16:31]
	ds_read_b128 v[4:7], v224 offset:96
	v_max_f32_e32 v248, v248, v250
	v_mov_b32_e32 v249, v248
	s_waitcnt lgkmcnt(4)
	v_mfma_f32_32x32x16_bf16 v[64:79], v[8:11], v[80:83], v[64:79]
	ds_read_b128 v[8:11], v224 offset:4704
	s_waitcnt lgkmcnt(4)
	v_mfma_f32_32x32x16_bf16 v[48:63], v[12:15], v[80:83], v[48:63]
	ds_read_b128 v[12:15], v224 offset:9312
	s_waitcnt lgkmcnt(4)
	v_mfma_f32_32x32x16_bf16 v[32:47], v[196:199], v[80:83], v[32:47]
	ds_read_b128 v[196:199], v224 offset:13920
	s_waitcnt lgkmcnt(4)
	v_mfma_f32_32x32x16_bf16 v[16:31], v[200:203], v[80:83], v[16:31]
	s_waitcnt lgkmcnt(3)
	v_mfma_f32_32x32x16_bf16 v[64:79], v[4:7], v[88:91], v[64:79]
	s_waitcnt lgkmcnt(2)
	v_mfma_f32_32x32x16_bf16 v[48:63], v[8:11], v[88:91], v[48:63]
	s_waitcnt lgkmcnt(1)
	v_mfma_f32_32x32x16_bf16 v[32:47], v[12:15], v[88:91], v[32:47]
	s_waitcnt lgkmcnt(0)
	v_mfma_f32_32x32x16_bf16 v[16:31], v[196:199], v[88:91], v[16:31]
	v_add_f32_e32 v0, v244, v246
	v_add_f32_e32 v241, v241, v0
	v_permlane32_swap_b32 v248, v249
	v_max_f32_e32 v174, v248, v249
	s_setprio 0
	s_cmp_lg_u32 s32, 0
	s_cbranch_scc1 .Lstg_post6
	s_waitcnt lgkmcnt(0)
	s_barrier

; #define LAS __attribute__((address_space(3)))
; DI unsigned cvt_pk(float lo, float hi) { unsigned r; asm volatile("v_cvt_pk_bf16_f32 %0, %1, %2" : "=v"(r) : "v"(lo), "v"(hi)); return r; }
; DI float fexp2(float x) { return __builtin_amdgcn_exp2f(x); }
; template <int DK, int DV, int MODE> ...
;     ...
;   auto part2 = [&](f32x16 (&st)[2], int t) __attribute__((always_inline)) {
;     float ps0 = 0.f, ps1 = 0.f, ps2 = 0.f, ps3 = 0.f;
; #pragma unroll
;     for (int kb = 0; kb < 2; ++kb)
; #pragma unroll
;       for (int i = 0; i < 16; i += 4) {
;         const float p0 = fexp2(st[kb][i]), p1 = fexp2(st[kb][i + 1]), p2 = fexp2(st[kb][i + 2]), p3 = fexp2(st[kb][i + 3]);
;         st[kb][i] = p0; st[kb][i + 1] = p1; st[kb][i + 2] = p2; st[kb][i + 3] = p3; ps0 += p0; ps1 += p1; ps2 += p2; ps3 += p3;
;       }
;     lsum += (ps0 + ps1) + (ps2 + ps3);
;     bf16x8 pf[2][2];
; #pragma unroll
;     for (int kb = 0; kb < 2; ++kb)
; #pragma unroll
;       for (int s = 0; s < 2; ++s) { u32x4 pp; pp.x = cvt_pk(st[kb][8 * s], st[kb][8 * s + 1]); pp.y = cvt_pk(st[kb][8 * s + 2], st[kb][8 * s + 3]); pp.z = cvt_pk(st[kb][8 * s + 4], st[kb][8 * s + 5]); pp.w = cvt_pk(st[kb][8 * s + 6], st[kb][8 * s + 7]); pf[kb][s] = __builtin_bit_cast(bf16x8, pp); }
; #pragma unroll
;     for (int db = 0; db < DV / 32; ++db)
; #pragma unroll
;       for (int kb = 0; kb < 2; ++kb)
; #pragma unroll
;         for (int s = 0; s < 2; ++s) {
;           if (MODE == 1 && ((kb == 1 && s == 1 && cwu == 0) || (kb == 0 && s == 0 && cwu != 0))) continue;
;           const bf16x8 vf = *(const LAS bf16x8*)(lds + ATT_VB + (t & 3) * VBUF + (32 * db + r) * VSTR + (2 * kb + s) * 32 + hh * 16);
;           O[db] = __builtin_amdgcn_mfma_f32_32x32x16_bf16(vf, pf[kb][s], O[db], 0, 0, 0);
;         }
;   };
.Lstg_pre7:
	s_and_b32 s40, s69, 2
	s_mulk_i32 s40, 0x2400
	s_mulk_i32 s70, 0x4800
	v_add_u32_e32 v3, s40, v235
	v_add_u32_e32 v224, s70, v237
	v_add_u32_e32 v224, 0xd000, v224
	ds_read_b128 v[4:7], v3
	ds_read_b128 v[8:11], v3 offset:32
	ds_read_b128 v[12:15], v3 offset:64
	ds_read_b128 v[196:199], v3 offset:96
	ds_read_b128 v[200:203], v3 offset:4608
	v_add_u32_e32 v0, 0x80, v242
	v_cmp_gt_i32_e32 vcc, s78, v0
	v_exp_f32_e32 v128, v128
	v_exp_f32_e32 v129, v129
	v_cndmask_b32_e32 v2, 0, v233, vcc
	v_cmp_lt_i32_e32 vcc, s77, v0
	v_exp_f32_e32 v130, v130
	v_exp_f32_e32 v131, v131
	v_cndmask_b32_e32 v0, v2, v234, vcc
	v_cmp_neq_f32_e32 vcc, s53, v193
	v_exp_f32_e32 v132, v132
	v_exp_f32_e32 v133, v133
	v_cndmask_b32_e32 v192, 0, v193, vcc
	v_sub_f32_e32 v80, v0, v192
	v_mov_b32_e32 v81, v80
	v_mov_b32_e32 v82, v80
	v_mov_b32_e32 v83, v80
	v_mov_b32_e32 v84, v80
	v_mov_b32_e32 v85, v80
	v_mov_b32_e32 v86, v80
	v_mov_b32_e32 v87, v80
	v_mov_b32_e32 v88, v80
	v_mov_b32_e32 v89, v80
	v_mov_b32_e32 v90, v80
	v_mov_b32_e32 v91, v80
	v_mov_b32_e32 v92, v80
	v_mov_b32_e32 v93, v80
	v_mov_b32_e32 v94, v80
	v_mov_b32_e32 v95, v80
	v_exp_f32_e32 v134, v134
	v_exp_f32_e32 v135, v135
	s_waitcnt lgkmcnt(4)
	v_mfma_f32_32x32x16_bf16 v[96:111], v[4:7], v[144:147], v[80:95]
	ds_read_b128 v[4:7], v3 offset:4640
	v_add_f32_e32 v244, v128, v132
	v_add_f32_e32 v245, v129, v133
	v_add_f32_e32 v246, v130, v134
	v_add_f32_e32 v247, v131, v135
	v_cvt_pk_bf16_f32 v128, v128, v129
	v_cvt_pk_bf16_f32 v129, v130, v131
	v_cvt_pk_bf16_f32 v130, v132, v133
	s_waitcnt lgkmcnt(4)
	v_mfma_f32_32x32x16_bf16 v[96:111], v[8:11], v[148:151], v[96:111]
	ds_read_b128 v[8:11], v3 offset:4672
	v_cvt_pk_bf16_f32 v131, v134, v135
	v_exp_f32_e32 v136, v136
	v_exp_f32_e32 v137, v137
	v_exp_f32_e32 v138, v138
	s_waitcnt lgkmcnt(4)
	v_mfma_f32_32x32x16_bf16 v[96:111], v[12:15], v[152:155], v[96:111]
	ds_read_b128 v[12:15], v3 offset:4704
	v_exp_f32_e32 v139, v139
	v_exp_f32_e32 v140, v140
	v_exp_f32_e32 v141, v141
	v_exp_f32_e32 v142, v142
	s_waitcnt lgkmcnt(4)
	v_mfma_f32_32x32x16_bf16 v[96:111], v[196:199], v[156:159], v[96:111]
	ds_read_b128 v[196:199], v224
	v_exp_f32_e32 v143, v143
	v_add_f32_e32 v244, v136, v244
	v_add_f32_e32 v245, v137, v245
	v_add_f32_e32 v246, v138, v246
	v_add_f32_e32 v247, v139, v247
	v_add_f32_e32 v244, v140, v244
	s_waitcnt lgkmcnt(4)
	v_mfma_f32_32x32x16_bf16 v[80:95], v[200:203], v[144:147], v[80:95]
	ds_read_b128 v[200:203], v224 offset:4608
	v_add_f32_e32 v245, v141, v245
	v_add_f32_e32 v246, v142, v246
	v_add_f32_e32 v247, v143, v247
	v_cvt_pk_bf16_f32 v136, v136, v137
	v_cvt_pk_bf16_f32 v137, v138, v139
	v_cvt_pk_bf16_f32 v138, v140, v141
	v_cvt_pk_bf16_f32 v139, v142, v143
	s_waitcnt lgkmcnt(4)
	v_mfma_f32_32x32x16_bf16 v[80:95], v[4:7], v[148:151], v[80:95]
	ds_read_b128 v[4:7], v224 offset:9216
	v_exp_f32_e32 v112, v112
	v_exp_f32_e32 v113, v113
	v_exp_f32_e32 v114, v114
	v_exp_f32_e32 v115, v115
	s_waitcnt lgkmcnt(4)
	v_mfma_f32_32x32x16_bf16 v[80:95], v[8:11], v[152:155], v[80:95]
	ds_read_b128 v[8:11], v224 offset:13824
	v_exp_f32_e32 v116, v116
	v_exp_f32_e32 v117, v117
	v_exp_f32_e32 v118, v118
	v_exp_f32_e32 v119, v119
	s_waitcnt lgkmcnt(4)
	v_mfma_f32_32x32x16_bf16 v[80:95], v[12:15], v[156:159], v[80:95]
	ds_read_b128 v[12:15], v224 offset:32
	v_add_f32_e32 v244, v112, v244
	v_add_f32_e32 v245, v113, v245
	v_add_f32_e32 v246, v114, v246
	v_add_f32_e32 v247, v115, v247
	v_add_f32_e32 v244, v116, v244
	v_add_f32_e32 v245, v117, v245
	v_add_f32_e32 v246, v118, v246
	s_waitcnt lgkmcnt(4)
	v_mfma_f32_32x32x16_bf16 v[64:79], v[196:199], v[128:131], v[64:79]
	ds_read_b128 v[196:199], v224 offset:4640
	v_add_f32_e32 v247, v119, v247
	v_cvt_pk_bf16_f32 v112, v112, v113
	v_cvt_pk_bf16_f32 v113, v114, v115
	v_cvt_pk_bf16_f32 v114, v116, v117
	v_cvt_pk_bf16_f32 v115, v118, v119
	v_exp_f32_e32 v120, v120
	s_waitcnt lgkmcnt(4)
	v_mfma_f32_32x32x16_bf16 v[48:63], v[200:203], v[128:131], v[48:63]
	ds_read_b128 v[200:203], v224 offset:9248
	v_exp_f32_e32 v121, v121
	v_exp_f32_e32 v122, v122
	v_exp_f32_e32 v123, v123
	v_exp_f32_e32 v124, v124
	s_waitcnt lgkmcnt(4)
	v_mfma_f32_32x32x16_bf16 v[32:47], v[4:7], v[128:131], v[32:47]
	ds_read_b128 v[4:7], v224 offset:13856
	v_exp_f32_e32 v125, v125
	v_exp_f32_e32 v126, v126
	v_exp_f32_e32 v127, v127
	v_add_f32_e32 v244, v120, v244
	s_waitcnt lgkmcnt(4)
	v_mfma_f32_32x32x16_bf16 v[16:31], v[8:11], v[128:131], v[16:31]
	ds_read_b128 v[8:11], v224 offset:64
	v_add_f32_e32 v245, v121, v245
	v_add_f32_e32 v246, v122, v246
	v_add_f32_e32 v247, v123, v247
	v_add_f32_e32 v244, v124, v244
	v_add_f32_e32 v245, v125, v245
	v_add_f32_e32 v246, v126, v246
	v_add_f32_e32 v247, v127, v247
	s_waitcnt lgkmcnt(4)
	v_mfma_f32_32x32x16_bf16 v[64:79], v[12:15], v[136:139], v[64:79]
	ds_read_b128 v[12:15], v224 offset:4672
	v_cvt_pk_bf16_f32 v120, v120, v121
	v_cvt_pk_bf16_f32 v121, v122, v123
	v_cvt_pk_bf16_f32 v122, v124, v125
	v_cvt_pk_bf16_f32 v123, v126, v127
	v_add_f32_e32 v244, v244, v245
	v_add_f32_e32 v246, v246, v247
	v_max3_f32 v248, v96, v97, v98
	s_waitcnt lgkmcnt(4)
	v_mfma_f32_32x32x16_bf16 v[48:63], v[196:199], v[136:139], v[48:63]
	ds_read_b128 v[196:199], v224 offset:9280
	v_max3_f32 v249, v103, v104, v105
	v_max3_f32 v248, v248, v99, v100
	v_max3_f32 v249, v249, v106, v107
	v_max3_f32 v248, v248, v101, v102
	v_max3_f32 v249, v249, v108, v109
	v_max3_f32 v250, v80, v81, v82
	v_max3_f32 v251, v87, v88, v89
	s_waitcnt lgkmcnt(4)
	v_mfma_f32_32x32x16_bf16 v[32:47], v[200:203], v[136:139], v[32:47]
	ds_read_b128 v[200:203], v224 offset:13888
	v_max3_f32 v250, v250, v83, v84
	v_max3_f32 v251, v251, v90, v91
	v_max3_f32 v250, v250, v85, v86
	v_max3_f32 v251, v251, v92, v93
	v_max3_f32 v248, v248, v249, v110
	v_max3_f32 v250, v250, v251, v94
	v_max3_f32 v248, v248, v111, v95
	s_waitcnt lgkmcnt(4)
	v_mfma_f32_32x32x16_bf16 v[16:31], v[4:7], v[136:139], v[16:31]
	ds_read_b128 v[4:7], v224 offset:96
	v_max_f32_e32 v248, v248, v250
	v_mov_b32_e32 v249, v248
	s_waitcnt lgkmcnt(4)
	v_mfma_f32_32x32x16_bf16 v[64:79], v[8:11], v[112:115], v[64:79]
	ds_read_b128 v[8:11], v224 offset:4704
	s_waitcnt lgkmcnt(4)
	v_mfma_f32_32x32x16_bf16 v[48:63], v[12:15], v[112:115], v[48:63]
	ds_read_b128 v[12:15], v224 offset:9312
	s_waitcnt lgkmcnt(4)
	v_mfma_f32_32x32x16_bf16 v[32:47], v[196:199], v[112:115], v[32:47]
	ds_read_b128 v[196:199], v224 offset:13920
	s_waitcnt lgkmcnt(4)
	v_mfma_f32_32x32x16_bf16 v[16:31], v[200:203], v[112:115], v[16:31]
	s_waitcnt lgkmcnt(3)
	v_mfma_f32_32x32x16_bf16 v[64:79], v[4:7], v[120:123], v[64:79]
	s_waitcnt lgkmcnt(2)
	v_mfma_f32_32x32x16_bf16 v[48:63], v[8:11], v[120:123], v[48:63]
	s_waitcnt lgkmcnt(1)
	v_mfma_f32_32x32x16_bf16 v[32:47], v[12:15], v[120:123], v[32:47]
	s_waitcnt lgkmcnt(0)
	v_mfma_f32_32x32x16_bf16 v[16:31], v[196:199], v[120:123], v[16:31]
	v_add_f32_e32 v0, v244, v246
	v_add_f32_e32 v241, v241, v0
	v_permlane32_swap_b32 v248, v249
	v_max_f32_e32 v174, v248, v249
	s_setprio 0
	s_cmp_lg_u32 s32, 0
	s_cbranch_scc1 .Lstg_post8
	s_waitcnt lgkmcnt(0)
	s_barrier

; #define LAS __attribute__((address_space(3)))
; DI unsigned cvt_pk(float lo, float hi) { unsigned r; asm volatile("v_cvt_pk_bf16_f32 %0, %1, %2" : "=v"(r) : "v"(lo), "v"(hi)); return r; }
; DI float fexp2(float x) { return __builtin_amdgcn_exp2f(x); }
; template <int DK, int DV, int MODE> ...
;     ...
;   auto part2 = [&](f32x16 (&st)[2], int t) __attribute__((always_inline)) {
;     float ps0 = 0.f, ps1 = 0.f, ps2 = 0.f, ps3 = 0.f;
; #pragma unroll
;     for (int kb = 0; kb < 2; ++kb)
; #pragma unroll
;       for (int i = 0; i < 16; i += 4) {
;         const float p0 = fexp2(st[kb][i]), p1 = fexp2(st[kb][i + 1]), p2 = fexp2(st[kb][i + 2]), p3 = fexp2(st[kb][i + 3]);
;         st[kb][i] = p0; st[kb][i + 1] = p1; st[kb][i + 2] = p2; st[kb][i + 3] = p3; ps0 += p0; ps1 += p1; ps2 += p2; ps3 += p3;
;       }
;     lsum += (ps0 + ps1) + (ps2 + ps3);
;     bf16x8 pf[2][2];
; #pragma unroll
;     for (int kb = 0; kb < 2; ++kb)
; #pragma unroll
;       for (int s = 0; s < 2; ++s) { u32x4 pp; pp.x = cvt_pk(st[kb][8 * s], st[kb][8 * s + 1]); pp.y = cvt_pk(st[kb][8 * s + 2], st[kb][8 * s + 3]); pp.z = cvt_pk(st[kb][8 * s + 4], st[kb][8 * s + 5]); pp.w = cvt_pk(st[kb][8 * s + 6], st[kb][8 * s + 7]); pf[kb][s] = __builtin_bit_cast(bf16x8, pp); }
; #pragma unroll
;     for (int db = 0; db < DV / 32; ++db)
; #pragma unroll
;       for (int kb = 0; kb < 2; ++kb)
; #pragma unroll
;         for (int s = 0; s < 2; ++s) {
;           if (MODE == 1 && ((kb == 1 && s == 1 && cwu == 0) || (kb == 0 && s == 0 && cwu != 0))) continue;
;           const bf16x8 vf = *(const LAS bf16x8*)(lds + ATT_VB + (t & 3) * VBUF + (32 * db + r) * VSTR + (2 * kb + s) * 32 + hh * 16);
;           O[db] = __builtin_amdgcn_mfma_f32_32x32x16_bf16(vf, pf[kb][s], O[db], 0, 0, 0);
;         }
;   };
.Lstg_pre9:
	s_add_i32 s28, s41, -4
	s_and_b32 s34, s28, 3
	s_mul_i32 s29, s34, 0x2400
	v_add_u32_e32 v3, s29, v233
	s_and_b32 s35, s50, 2
	s_mul_i32 s29, s35, 0x4800
	v_add_u32_e32 v224, s29, v235
	v_add_u32_e32 v224, 0xd000, v224
	ds_read_b128 v[4:7], v3
	ds_read_b128 v[8:11], v3 offset:32
	ds_read_b128 v[12:15], v3 offset:64
	ds_read_b128 v[196:199], v3 offset:96
	ds_read_b128 v[200:203], v3 offset:4608
	v_add_u32_e32 v0, 64, v240
	v_cmp_gt_i32_e64 s[46:47], s78, v0
	v_cmp_lt_i32_e32 vcc, s77, v0
	v_exp_f32_e32 v96, v96
	v_exp_f32_e32 v97, v97
	v_cndmask_b32_e64 v0, 0, v231, s[46:47]
	v_exp_f32_e32 v98, v98
	v_cndmask_b32_e32 v0, v0, v232, vcc
	v_cmp_neq_f32_e32 vcc, s53, v191
	v_exp_f32_e32 v99, v99
	v_exp_f32_e32 v100, v100
	v_exp_f32_e32 v101, v101
	v_cndmask_b32_e32 v2, 0, v191, vcc
	v_sub_f32_e32 v112, v0, v2
	v_mov_b32_e32 v113, v112
	v_mov_b32_e32 v114, v112
	v_mov_b32_e32 v115, v112
	v_mov_b32_e32 v116, v112
	v_mov_b32_e32 v117, v112
	v_mov_b32_e32 v118, v112
	v_mov_b32_e32 v119, v112
	v_mov_b32_e32 v120, v112
	v_mov_b32_e32 v121, v112
	v_mov_b32_e32 v122, v112
	v_mov_b32_e32 v123, v112
	v_mov_b32_e32 v124, v112
	v_mov_b32_e32 v125, v112
	v_mov_b32_e32 v126, v112
	v_mov_b32_e32 v127, v112
	v_exp_f32_e32 v102, v102
	v_exp_f32_e32 v103, v103
	s_waitcnt lgkmcnt(4)
	v_mfma_f32_32x32x16_bf16 v[128:143], v[4:7], v[144:147], v[112:127]
	ds_read_b128 v[4:7], v3 offset:4640
	v_add_f32_e32 v244, v96, v100
	v_add_f32_e32 v245, v97, v101
	v_add_f32_e32 v246, v98, v102
	v_add_f32_e32 v247, v99, v103
	v_cvt_pk_bf16_f32 v96, v96, v97
	v_cvt_pk_bf16_f32 v97, v98, v99
	v_cvt_pk_bf16_f32 v98, v100, v101
	s_waitcnt lgkmcnt(4)
	v_mfma_f32_32x32x16_bf16 v[128:143], v[8:11], v[148:151], v[128:143]
	ds_read_b128 v[8:11], v3 offset:4672
	v_cvt_pk_bf16_f32 v99, v102, v103
	v_exp_f32_e32 v104, v104
	v_exp_f32_e32 v105, v105
	v_exp_f32_e32 v106, v106
	s_waitcnt lgkmcnt(4)
	v_mfma_f32_32x32x16_bf16 v[128:143], v[12:15], v[152:155], v[128:143]
	ds_read_b128 v[12:15], v3 offset:4704
	v_exp_f32_e32 v107, v107
	v_exp_f32_e32 v108, v108
	v_exp_f32_e32 v109, v109
	v_exp_f32_e32 v110, v110
	s_waitcnt lgkmcnt(4)
	v_mfma_f32_32x32x16_bf16 v[128:143], v[196:199], v[156:159], v[128:143]
	ds_read_b128 v[196:199], v224
	v_exp_f32_e32 v111, v111
	v_add_f32_e32 v244, v104, v244
	v_add_f32_e32 v245, v105, v245
	v_add_f32_e32 v246, v106, v246
	v_add_f32_e32 v247, v107, v247
	v_add_f32_e32 v244, v108, v244
	s_waitcnt lgkmcnt(4)
	v_mfma_f32_32x32x16_bf16 v[112:127], v[200:203], v[144:147], v[112:127]
	ds_read_b128 v[200:203], v224 offset:4608
	v_add_f32_e32 v245, v109, v245
	v_add_f32_e32 v246, v110, v246
	v_add_f32_e32 v247, v111, v247
	v_cvt_pk_bf16_f32 v104, v104, v105
	v_cvt_pk_bf16_f32 v105, v106, v107
	v_cvt_pk_bf16_f32 v106, v108, v109
	v_cvt_pk_bf16_f32 v107, v110, v111
	s_waitcnt lgkmcnt(4)
	v_mfma_f32_32x32x16_bf16 v[112:127], v[4:7], v[148:151], v[112:127]
	ds_read_b128 v[4:7], v224 offset:9216
	v_exp_f32_e32 v80, v80
	v_exp_f32_e32 v81, v81
	v_exp_f32_e32 v82, v82
	v_exp_f32_e32 v83, v83
	s_waitcnt lgkmcnt(4)
	v_mfma_f32_32x32x16_bf16 v[112:127], v[8:11], v[152:155], v[112:127]
	ds_read_b128 v[8:11], v224 offset:13824
	v_exp_f32_e32 v84, v84
	v_exp_f32_e32 v85, v85
	v_exp_f32_e32 v86, v86
	v_exp_f32_e32 v87, v87
	s_waitcnt lgkmcnt(4)
	v_mfma_f32_32x32x16_bf16 v[112:127], v[12:15], v[156:159], v[112:127]
	ds_read_b128 v[12:15], v224 offset:32
	v_add_f32_e32 v244, v80, v244
	v_add_f32_e32 v245, v81, v245
	v_add_f32_e32 v246, v82, v246
	v_add_f32_e32 v247, v83, v247
	v_add_f32_e32 v244, v84, v244
	v_add_f32_e32 v245, v85, v245
	v_add_f32_e32 v246, v86, v246
	s_waitcnt lgkmcnt(4)
	v_mfma_f32_32x32x16_bf16 v[64:79], v[196:199], v[96:99], v[64:79]
	ds_read_b128 v[196:199], v224 offset:4640
	v_add_f32_e32 v247, v87, v247
	v_cvt_pk_bf16_f32 v80, v80, v81
	v_cvt_pk_bf16_f32 v81, v82, v83
	v_cvt_pk_bf16_f32 v82, v84, v85
	v_cvt_pk_bf16_f32 v83, v86, v87
	v_exp_f32_e32 v88, v88
	s_waitcnt lgkmcnt(4)
	v_mfma_f32_32x32x16_bf16 v[48:63], v[200:203], v[96:99], v[48:63]
	ds_read_b128 v[200:203], v224 offset:9248
	v_exp_f32_e32 v89, v89
	v_exp_f32_e32 v90, v90
	v_exp_f32_e32 v91, v91
	v_exp_f32_e32 v92, v92
	s_waitcnt lgkmcnt(4)
	v_mfma_f32_32x32x16_bf16 v[32:47], v[4:7], v[96:99], v[32:47]
	ds_read_b128 v[4:7], v224 offset:13856
	v_exp_f32_e32 v93, v93
	v_exp_f32_e32 v94, v94
	v_exp_f32_e32 v95, v95
	v_add_f32_e32 v244, v88, v244
	s_waitcnt lgkmcnt(4)
	v_mfma_f32_32x32x16_bf16 v[16:31], v[8:11], v[96:99], v[16:31]
	ds_read_b128 v[8:11], v224 offset:64
	v_add_f32_e32 v245, v89, v245
	v_add_f32_e32 v246, v90, v246
	v_add_f32_e32 v247, v91, v247
	v_add_f32_e32 v244, v92, v244
	v_add_f32_e32 v245, v93, v245
	v_add_f32_e32 v246, v94, v246
	v_add_f32_e32 v247, v95, v247
	s_waitcnt lgkmcnt(4)
	v_mfma_f32_32x32x16_bf16 v[64:79], v[12:15], v[104:107], v[64:79]
	ds_read_b128 v[12:15], v224 offset:4672
	v_cvt_pk_bf16_f32 v88, v88, v89
	v_cvt_pk_bf16_f32 v89, v90, v91
	v_cvt_pk_bf16_f32 v90, v92, v93
	v_cvt_pk_bf16_f32 v91, v94, v95
	v_add_f32_e32 v244, v244, v245
	v_add_f32_e32 v246, v246, v247
	v_max3_f32 v248, v128, v129, v130
	s_waitcnt lgkmcnt(4)
	v_mfma_f32_32x32x16_bf16 v[48:63], v[196:199], v[104:107], v[48:63]
	ds_read_b128 v[196:199], v224 offset:9280
	v_max3_f32 v249, v135, v136, v137
	v_max3_f32 v248, v248, v131, v132
	v_max3_f32 v249, v249, v138, v139
	v_max3_f32 v248, v248, v133, v134
	v_max3_f32 v249, v249, v140, v141
	v_max3_f32 v250, v112, v113, v114
	v_max3_f32 v251, v119, v120, v121
	s_waitcnt lgkmcnt(4)
	v_mfma_f32_32x32x16_bf16 v[32:47], v[200:203], v[104:107], v[32:47]
	ds_read_b128 v[200:203], v224 offset:13888
	v_max3_f32 v250, v250, v115, v116
	v_max3_f32 v251, v251, v122, v123
	v_max3_f32 v250, v250, v117, v118
	v_max3_f32 v251, v251, v124, v125
	v_max3_f32 v248, v248, v249, v142
	v_max3_f32 v250, v250, v251, v126
	v_max3_f32 v248, v248, v143, v127
	s_waitcnt lgkmcnt(4)
	v_mfma_f32_32x32x16_bf16 v[16:31], v[4:7], v[104:107], v[16:31]
	ds_read_b128 v[4:7], v224 offset:96
	v_max_f32_e32 v248, v248, v250
	v_mov_b32_e32 v249, v248
	s_waitcnt lgkmcnt(4)
	v_mfma_f32_32x32x16_bf16 v[64:79], v[8:11], v[80:83], v[64:79]
	ds_read_b128 v[8:11], v224 offset:4704
	s_waitcnt lgkmcnt(4)
	v_mfma_f32_32x32x16_bf16 v[48:63], v[12:15], v[80:83], v[48:63]
	ds_read_b128 v[12:15], v224 offset:9312
	s_waitcnt lgkmcnt(4)
	v_mfma_f32_32x32x16_bf16 v[32:47], v[196:199], v[80:83], v[32:47]
	ds_read_b128 v[196:199], v224 offset:13920
	s_waitcnt lgkmcnt(4)
	v_mfma_f32_32x32x16_bf16 v[16:31], v[200:203], v[80:83], v[16:31]
	s_waitcnt lgkmcnt(3)
	v_mfma_f32_32x32x16_bf16 v[64:79], v[4:7], v[88:91], v[64:79]
	s_waitcnt lgkmcnt(2)
	v_mfma_f32_32x32x16_bf16 v[48:63], v[8:11], v[88:91], v[48:63]
	s_waitcnt lgkmcnt(1)
	v_mfma_f32_32x32x16_bf16 v[32:47], v[12:15], v[88:91], v[32:47]
	s_waitcnt lgkmcnt(0)
	v_mfma_f32_32x32x16_bf16 v[16:31], v[196:199], v[88:91], v[16:31]
	v_add_f32_e32 v0, v244, v246
	v_add_f32_e32 v239, v239, v0
	v_permlane32_swap_b32 v248, v249
	v_max_f32_e32 v174, v248, v249
	s_setprio 0
	s_cmp_lg_u32 s32, 0
	s_cbranch_scc1 .Lstg_post10
	s_waitcnt lgkmcnt(0)
	s_barrier

; #define LAS __attribute__((address_space(3)))
; DI unsigned cvt_pk(float lo, float hi) { unsigned r; asm volatile("v_cvt_pk_bf16_f32 %0, %1, %2" : "=v"(r) : "v"(lo), "v"(hi)); return r; }
; DI float fexp2(float x) { return __builtin_amdgcn_exp2f(x); }
; template <int DK, int DV, int MODE> ...
;     ...
;   auto part2 = [&](f32x16 (&st)[2], int t) __attribute__((always_inline)) {
;     float ps0 = 0.f, ps1 = 0.f, ps2 = 0.f, ps3 = 0.f;
; #pragma unroll
;     for (int kb = 0; kb < 2; ++kb)
; #pragma unroll
;       for (int i = 0; i < 16; i += 4) {
;         const float p0 = fexp2(st[kb][i]), p1 = fexp2(st[kb][i + 1]), p2 = fexp2(st[kb][i + 2]), p3 = fexp2(st[kb][i + 3]);
;         st[kb][i] = p0; st[kb][i + 1] = p1; st[kb][i + 2] = p2; st[kb][i + 3] = p3; ps0 += p0; ps1 += p1; ps2 += p2; ps3 += p3;
;       }
;     lsum += (ps0 + ps1) + (ps2 + ps3);
;     bf16x8 pf[2][2];
; #pragma unroll
;     for (int kb = 0; kb < 2; ++kb)
; #pragma unroll
;       for (int s = 0; s < 2; ++s) { u32x4 pp; pp.x = cvt_pk(st[kb][8 * s], st[kb][8 * s + 1]); pp.y = cvt_pk(st[kb][8 * s + 2], st[kb][8 * s + 3]); pp.z = cvt_pk(st[kb][8 * s + 4], st[kb][8 * s + 5]); pp.w = cvt_pk(st[kb][8 * s + 6], st[kb][8 * s + 7]); pf[kb][s] = __builtin_bit_cast(bf16x8, pp); }
; #pragma unroll
;     for (int db = 0; db < DV / 32; ++db)
; #pragma unroll
;       for (int kb = 0; kb < 2; ++kb)
; #pragma unroll
;         for (int s = 0; s < 2; ++s) {
;           if (MODE == 1 && ((kb == 1 && s == 1 && cwu == 0) || (kb == 0 && s == 0 && cwu != 0))) continue;
;           const bf16x8 vf = *(const LAS bf16x8*)(lds + ATT_VB + (t & 3) * VBUF + (32 * db + r) * VSTR + (2 * kb + s) * 32 + hh * 16);
;           O[db] = __builtin_amdgcn_mfma_f32_32x32x16_bf16(vf, pf[kb][s], O[db], 0, 0, 0);
;         }
;   };
.Lstg_pre11:
	s_and_b32 s20, s48, 2
	s_mulk_i32 s20, 0x2400
	s_mulk_i32 s34, 0x4800
	v_add_u32_e32 v3, s20, v233
	v_add_u32_e32 v224, s34, v235
	v_add_u32_e32 v224, 0xd000, v224
	ds_read_b128 v[4:7], v3
	ds_read_b128 v[8:11], v3 offset:32
	ds_read_b128 v[12:15], v3 offset:64
	ds_read_b128 v[196:199], v3 offset:96
	ds_read_b128 v[200:203], v3 offset:4608
	v_add_u32_e32 v0, 0x80, v240
	v_cmp_gt_i32_e32 vcc, s78, v0
	v_exp_f32_e32 v128, v128
	v_exp_f32_e32 v129, v129
	v_cndmask_b32_e32 v2, 0, v231, vcc
	v_cmp_lt_i32_e32 vcc, s77, v0
	v_exp_f32_e32 v130, v130
	v_exp_f32_e32 v131, v131
	v_cndmask_b32_e32 v0, v2, v232, vcc
	v_cmp_neq_f32_e32 vcc, s53, v191
	v_exp_f32_e32 v132, v132
	v_exp_f32_e32 v133, v133
	v_cndmask_b32_e32 v190, 0, v191, vcc
	v_sub_f32_e32 v80, v0, v190
	v_mov_b32_e32 v81, v80
	v_mov_b32_e32 v82, v80
	v_mov_b32_e32 v83, v80
	v_mov_b32_e32 v84, v80
	v_mov_b32_e32 v85, v80
	v_mov_b32_e32 v86, v80
	v_mov_b32_e32 v87, v80
	v_mov_b32_e32 v88, v80
	v_mov_b32_e32 v89, v80
	v_mov_b32_e32 v90, v80
	v_mov_b32_e32 v91, v80
	v_mov_b32_e32 v92, v80
	v_mov_b32_e32 v93, v80
	v_mov_b32_e32 v94, v80
	v_mov_b32_e32 v95, v80
	v_exp_f32_e32 v134, v134
	v_exp_f32_e32 v135, v135
	s_waitcnt lgkmcnt(4)
	v_mfma_f32_32x32x16_bf16 v[96:111], v[4:7], v[144:147], v[80:95]
	ds_read_b128 v[4:7], v3 offset:4640
	v_add_f32_e32 v244, v128, v132
	v_add_f32_e32 v245, v129, v133
	v_add_f32_e32 v246, v130, v134
	v_add_f32_e32 v247, v131, v135
	v_cvt_pk_bf16_f32 v128, v128, v129
	v_cvt_pk_bf16_f32 v129, v130, v131
	v_cvt_pk_bf16_f32 v130, v132, v133
	s_waitcnt lgkmcnt(4)
	v_mfma_f32_32x32x16_bf16 v[96:111], v[8:11], v[148:151], v[96:111]
	ds_read_b128 v[8:11], v3 offset:4672
	v_cvt_pk_bf16_f32 v131, v134, v135
	v_exp_f32_e32 v136, v136
	v_exp_f32_e32 v137, v137
	v_exp_f32_e32 v138, v138
	s_waitcnt lgkmcnt(4)
	v_mfma_f32_32x32x16_bf16 v[96:111], v[12:15], v[152:155], v[96:111]
	ds_read_b128 v[12:15], v3 offset:4704
	v_exp_f32_e32 v139, v139
	v_exp_f32_e32 v140, v140
	v_exp_f32_e32 v141, v141
	v_exp_f32_e32 v142, v142
	s_waitcnt lgkmcnt(4)
	v_mfma_f32_32x32x16_bf16 v[96:111], v[196:199], v[156:159], v[96:111]
	ds_read_b128 v[196:199], v224
	v_exp_f32_e32 v143, v143
	v_add_f32_e32 v244, v136, v244
	v_add_f32_e32 v245, v137, v245
	v_add_f32_e32 v246, v138, v246
	v_add_f32_e32 v247, v139, v247
	v_add_f32_e32 v244, v140, v244
	s_waitcnt lgkmcnt(4)
	v_mfma_f32_32x32x16_bf16 v[80:95], v[200:203], v[144:147], v[80:95]
	ds_read_b128 v[200:203], v224 offset:4608
	v_add_f32_e32 v245, v141, v245
	v_add_f32_e32 v246, v142, v246
	v_add_f32_e32 v247, v143, v247
	v_cvt_pk_bf16_f32 v136, v136, v137
	v_cvt_pk_bf16_f32 v137, v138, v139
	v_cvt_pk_bf16_f32 v138, v140, v141
	v_cvt_pk_bf16_f32 v139, v142, v143
	s_waitcnt lgkmcnt(4)
	v_mfma_f32_32x32x16_bf16 v[80:95], v[4:7], v[148:151], v[80:95]
	ds_read_b128 v[4:7], v224 offset:9216
	v_exp_f32_e32 v112, v112
	v_exp_f32_e32 v113, v113
	v_exp_f32_e32 v114, v114
	v_exp_f32_e32 v115, v115
	s_waitcnt lgkmcnt(4)
	v_mfma_f32_32x32x16_bf16 v[80:95], v[8:11], v[152:155], v[80:95]
	ds_read_b128 v[8:11], v224 offset:13824
	v_exp_f32_e32 v116, v116
	v_exp_f32_e32 v117, v117
	v_exp_f32_e32 v118, v118
	v_exp_f32_e32 v119, v119
	s_waitcnt lgkmcnt(4)
	v_mfma_f32_32x32x16_bf16 v[80:95], v[12:15], v[156:159], v[80:95]
	ds_read_b128 v[12:15], v224 offset:32
	v_add_f32_e32 v244, v112, v244
	v_add_f32_e32 v245, v113, v245
	v_add_f32_e32 v246, v114, v246
	v_add_f32_e32 v247, v115, v247
	v_add_f32_e32 v244, v116, v244
	v_add_f32_e32 v245, v117, v245
	v_add_f32_e32 v246, v118, v246
	s_waitcnt lgkmcnt(4)
	v_mfma_f32_32x32x16_bf16 v[64:79], v[196:199], v[128:131], v[64:79]
	ds_read_b128 v[196:199], v224 offset:4640
	v_add_f32_e32 v247, v119, v247
	v_cvt_pk_bf16_f32 v112, v112, v113
	v_cvt_pk_bf16_f32 v113, v114, v115
	v_cvt_pk_bf16_f32 v114, v116, v117
	v_cvt_pk_bf16_f32 v115, v118, v119
	v_exp_f32_e32 v120, v120
	s_waitcnt lgkmcnt(4)
	v_mfma_f32_32x32x16_bf16 v[48:63], v[200:203], v[128:131], v[48:63]
	ds_read_b128 v[200:203], v224 offset:9248
	v_exp_f32_e32 v121, v121
	v_exp_f32_e32 v122, v122
	v_exp_f32_e32 v123, v123
	v_exp_f32_e32 v124, v124
	s_waitcnt lgkmcnt(4)
	v_mfma_f32_32x32x16_bf16 v[32:47], v[4:7], v[128:131], v[32:47]
	ds_read_b128 v[4:7], v224 offset:13856
	v_exp_f32_e32 v125, v125
	v_exp_f32_e32 v126, v126
	v_exp_f32_e32 v127, v127
	v_add_f32_e32 v244, v120, v244
	s_waitcnt lgkmcnt(4)
	v_mfma_f32_32x32x16_bf16 v[16:31], v[8:11], v[128:131], v[16:31]
	ds_read_b128 v[8:11], v224 offset:64
	v_add_f32_e32 v245, v121, v245
	v_add_f32_e32 v246, v122, v246
	v_add_f32_e32 v247, v123, v247
	v_add_f32_e32 v244, v124, v244
	v_add_f32_e32 v245, v125, v245
	v_add_f32_e32 v246, v126, v246
	v_add_f32_e32 v247, v127, v247
	s_waitcnt lgkmcnt(4)
	v_mfma_f32_32x32x16_bf16 v[64:79], v[12:15], v[136:139], v[64:79]
	ds_read_b128 v[12:15], v224 offset:4672
	v_cvt_pk_bf16_f32 v120, v120, v121
	v_cvt_pk_bf16_f32 v121, v122, v123
	v_cvt_pk_bf16_f32 v122, v124, v125
	v_cvt_pk_bf16_f32 v123, v126, v127
	v_add_f32_e32 v244, v244, v245
	v_add_f32_e32 v246, v246, v247
	v_max3_f32 v248, v96, v97, v98
	s_waitcnt lgkmcnt(4)
	v_mfma_f32_32x32x16_bf16 v[48:63], v[196:199], v[136:139], v[48:63]
	ds_read_b128 v[196:199], v224 offset:9280
	v_max3_f32 v249, v103, v104, v105
	v_max3_f32 v248, v248, v99, v100
	v_max3_f32 v249, v249, v106, v107
	v_max3_f32 v248, v248, v101, v102
	v_max3_f32 v249, v249, v108, v109
	v_max3_f32 v250, v80, v81, v82
	v_max3_f32 v251, v87, v88, v89
	s_waitcnt lgkmcnt(4)
	v_mfma_f32_32x32x16_bf16 v[32:47], v[200:203], v[136:139], v[32:47]
	ds_read_b128 v[200:203], v224 offset:13888
	v_max3_f32 v250, v250, v83, v84
	v_max3_f32 v251, v251, v90, v91
	v_max3_f32 v250, v250, v85, v86
	v_max3_f32 v251, v251, v92, v93
	v_max3_f32 v248, v248, v249, v110
	v_max3_f32 v250, v250, v251, v94
	v_max3_f32 v248, v248, v111, v95
	s_waitcnt lgkmcnt(4)
	v_mfma_f32_32x32x16_bf16 v[16:31], v[4:7], v[136:139], v[16:31]
	ds_read_b128 v[4:7], v224 offset:96
	v_max_f32_e32 v248, v248, v250
	v_mov_b32_e32 v249, v248
	s_waitcnt lgkmcnt(4)
	v_mfma_f32_32x32x16_bf16 v[64:79], v[8:11], v[112:115], v[64:79]
	ds_read_b128 v[8:11], v224 offset:4704
	s_waitcnt lgkmcnt(4)
	v_mfma_f32_32x32x16_bf16 v[48:63], v[12:15], v[112:115], v[48:63]
	ds_read_b128 v[12:15], v224 offset:9312
	s_waitcnt lgkmcnt(4)
	v_mfma_f32_32x32x16_bf16 v[32:47], v[196:199], v[112:115], v[32:47]
	ds_read_b128 v[196:199], v224 offset:13920
	s_waitcnt lgkmcnt(4)
	v_mfma_f32_32x32x16_bf16 v[16:31], v[200:203], v[112:115], v[16:31]
	s_waitcnt lgkmcnt(3)
	v_mfma_f32_32x32x16_bf16 v[64:79], v[4:7], v[120:123], v[64:79]
	s_waitcnt lgkmcnt(2)
	v_mfma_f32_32x32x16_bf16 v[48:63], v[8:11], v[120:123], v[48:63]
	s_waitcnt lgkmcnt(1)
	v_mfma_f32_32x32x16_bf16 v[32:47], v[12:15], v[120:123], v[32:47]
	s_waitcnt lgkmcnt(0)
	v_mfma_f32_32x32x16_bf16 v[16:31], v[196:199], v[120:123], v[16:31]
	v_add_f32_e32 v0, v244, v246
	v_add_f32_e32 v239, v239, v0
	v_permlane32_swap_b32 v248, v249
	v_max_f32_e32 v174, v248, v249
	s_setprio 0
	s_cmp_lg_u32 s32, 0
	s_cbranch_scc1 .Lstg_post12
	s_waitcnt lgkmcnt(0)
	s_barrier

; #define LAS __attribute__((address_space(3)))
; DI unsigned cvt_pk(float lo, float hi) { unsigned r; asm volatile("v_cvt_pk_bf16_f32 %0, %1, %2" : "=v"(r) : "v"(lo), "v"(hi)); return r; }
; DI float fexp2(float x) { return __builtin_amdgcn_exp2f(x); }
; template <int DK, int DV, int MODE> ...
;     ...
;   auto part2 = [&](f32x16 (&st)[2], int t) __attribute__((always_inline)) {
;     float ps0 = 0.f, ps1 = 0.f, ps2 = 0.f, ps3 = 0.f;
; #pragma unroll
;     for (int kb = 0; kb < 2; ++kb)
; #pragma unroll
;       for (int i = 0; i < 16; i += 4) {
;         const float p0 = fexp2(st[kb][i]), p1 = fexp2(st[kb][i + 1]), p2 = fexp2(st[kb][i + 2]), p3 = fexp2(st[kb][i + 3]);
;         st[kb][i] = p0; st[kb][i + 1] = p1; st[kb][i + 2] = p2; st[kb][i + 3] = p3; ps0 += p0; ps1 += p1; ps2 += p2; ps3 += p3;
;       }
;     lsum += (ps0 + ps1) + (ps2 + ps3);
;     bf16x8 pf[2][2];
; #pragma unroll
;     for (int kb = 0; kb < 2; ++kb)
; #pragma unroll
;       for (int s = 0; s < 2; ++s) { u32x4 pp; pp.x = cvt_pk(st[kb][8 * s], st[kb][8 * s + 1]); pp.y = cvt_pk(st[kb][8 * s + 2], st[kb][8 * s + 3]); pp.z = cvt_pk(st[kb][8 * s + 4], st[kb][8 * s + 5]); pp.w = cvt_pk(st[kb][8 * s + 6], st[kb][8 * s + 7]); pf[kb][s] = __builtin_bit_cast(bf16x8, pp); }
; #pragma unroll
;     for (int db = 0; db < DV / 32; ++db)
; #pragma unroll
;       for (int kb = 0; kb < 2; ++kb)
; #pragma unroll
;         for (int s = 0; s < 2; ++s) {
;           if (MODE == 1 && ((kb == 1 && s == 1 && cwu == 0) || (kb == 0 && s == 0 && cwu != 0))) continue;
;           const bf16x8 vf = *(const LAS bf16x8*)(lds + ATT_VB + (t & 3) * VBUF + (32 * db + r) * VSTR + (2 * kb + s) * 32 + hh * 16);
;           O[db] = __builtin_amdgcn_mfma_f32_32x32x16_bf16(vf, pf[kb][s], O[db], 0, 0, 0);
;         }
;   };
.Lfb_a0:
	s_add_i32 s25, s19, -4
	s_and_b32 s21, s25, 3
	s_mul_i32 s26, s21, 0x3400
	s_and_b32 s23, s23, 2
	v_add_u32_e32 v252, s26, v160
	s_mul_i32 s26, s23, 0x2400
	ds_read_b128 v[196:199], v252
	ds_read_b128 v[200:203], v252 offset:32
	ds_read_b128 v[216:219], v252 offset:64
	ds_read_b128 v[230:233], v252 offset:96
	ds_read_b128 v[234:237], v252 offset:128
	ds_read_b128 v[244:247], v252 offset:160
	v_add_u32_e32 v243, s26, v163
	v_add_u32_e32 v0, 64, v167
	v_cmp_gt_i32_e32 vcc, s78, v0
	v_exp_f32_e32 v50, v50
	v_exp_f32_e32 v51, v51
	v_cndmask_b32_e32 v66, 0, v158, vcc
	v_cmp_lt_i32_e32 vcc, s77, v0
	v_exp_f32_e32 v52, v52
	v_exp_f32_e32 v53, v53
	v_cndmask_b32_e32 v0, v66, v159, vcc
	v_cmp_neq_f32_e32 vcc, s53, v143
	v_exp_f32_e32 v54, v54
	v_exp_f32_e32 v55, v55
	v_cndmask_b32_e32 v144, 0, v143, vcc
	v_sub_f32_e32 v66, v0, v144
	v_mov_b32_e32 v67, v66
	v_mov_b32_e32 v68, v66
	v_mov_b32_e32 v69, v66
	v_mov_b32_e32 v70, v66
	v_mov_b32_e32 v71, v66
	v_mov_b32_e32 v72, v66
	v_mov_b32_e32 v73, v66
	v_mov_b32_e32 v74, v66
	v_mov_b32_e32 v75, v66
	v_mov_b32_e32 v76, v66
	v_mov_b32_e32 v77, v66
	v_mov_b32_e32 v78, v66
	v_mov_b32_e32 v79, v66
	v_mov_b32_e32 v80, v66
	v_mov_b32_e32 v81, v66
	v_exp_f32_e32 v56, v56
	v_exp_f32_e32 v57, v57
	s_waitcnt lgkmcnt(5)
	v_mfma_f32_32x32x16_bf16 v[82:97], v[196:199], v[98:101], v[66:81]
	ds_read_b128 v[196:199], v252 offset:6656
	v_exp_f32_e32 v58, v58
	v_exp_f32_e32 v59, v59
	v_exp_f32_e32 v60, v60
	v_exp_f32_e32 v61, v61
	s_waitcnt lgkmcnt(5)
	v_mfma_f32_32x32x16_bf16 v[82:97], v[200:203], v[102:105], v[82:97]
	ds_read_b128 v[200:203], v252 offset:6688
	v_exp_f32_e32 v62, v62
	v_exp_f32_e32 v63, v63
	v_exp_f32_e32 v64, v64
	v_exp_f32_e32 v65, v65
	s_waitcnt lgkmcnt(5)
	v_mfma_f32_32x32x16_bf16 v[82:97], v[216:219], v[106:109], v[82:97]
	ds_read_b128 v[216:219], v252 offset:6720
	v_exp_f32_e32 v34, v34
	v_exp_f32_e32 v35, v35
	v_cvt_pk_bf16_f32 v168, v50, v51
	v_exp_f32_e32 v36, v36
	s_waitcnt lgkmcnt(5)
	v_mfma_f32_32x32x16_bf16 v[82:97], v[230:233], v[110:113], v[82:97]
	ds_read_b128 v[230:233], v252 offset:6752
	v_exp_f32_e32 v37, v37
	v_cvt_pk_bf16_f32 v169, v52, v53
	v_exp_f32_e32 v38, v38
	v_exp_f32_e32 v39, v39
	s_waitcnt lgkmcnt(5)
	v_mfma_f32_32x32x16_bf16 v[82:97], v[234:237], v[114:117], v[82:97]
	ds_read_b128 v[234:237], v252 offset:6784
	v_cvt_pk_bf16_f32 v170, v54, v55
	v_exp_f32_e32 v40, v40
	v_exp_f32_e32 v41, v41
	v_cvt_pk_bf16_f32 v171, v56, v57
	v_exp_f32_e32 v42, v42
	s_waitcnt lgkmcnt(5)
	v_mfma_f32_32x32x16_bf16 v[82:97], v[244:247], v[118:121], v[82:97]
	ds_read_b128 v[244:247], v252 offset:6816
	v_exp_f32_e32 v43, v43
	v_cvt_pk_bf16_f32 v180, v58, v59
	v_exp_f32_e32 v44, v44
	v_exp_f32_e32 v45, v45
	s_waitcnt lgkmcnt(5)
	v_mfma_f32_32x32x16_bf16 v[66:81], v[196:199], v[98:101], v[66:81]
	ds_read_b128 v[196:199], v243 offset:53248
	v_cvt_pk_bf16_f32 v181, v60, v61
	v_exp_f32_e32 v46, v46
	v_exp_f32_e32 v47, v47
	v_cvt_pk_bf16_f32 v182, v62, v63
	v_exp_f32_e32 v48, v48
	s_waitcnt lgkmcnt(5)
	v_mfma_f32_32x32x16_bf16 v[66:81], v[200:203], v[102:105], v[66:81]
	ds_read_b128 v[200:203], v243 offset:57856
	v_exp_f32_e32 v49, v49
	v_cvt_pk_bf16_f32 v183, v64, v65
	v_add_f32_e32 v172, v50, v54
	v_add_f32_e32 v173, v51, v55
	v_add_f32_e32 v176, v52, v56
	v_add_f32_e32 v179, v53, v57
	s_waitcnt lgkmcnt(5)
	v_mfma_f32_32x32x16_bf16 v[66:81], v[216:219], v[106:109], v[66:81]
	ds_read_b128 v[216:219], v243 offset:53280
	v_add_f32_e32 v172, v58, v172
	v_add_f32_e32 v173, v59, v173
	v_add_f32_e32 v176, v60, v176
	v_add_f32_e32 v179, v61, v179
	v_add_f32_e32 v172, v62, v172
	v_add_f32_e32 v173, v63, v173
	v_add_f32_e32 v176, v64, v176
	s_waitcnt lgkmcnt(5)
	v_mfma_f32_32x32x16_bf16 v[66:81], v[230:233], v[110:113], v[66:81]
	ds_read_b128 v[230:233], v243 offset:57888
	v_add_f32_e32 v179, v65, v179
	v_cvt_pk_bf16_f32 v184, v34, v35
	v_cvt_pk_bf16_f32 v185, v36, v37
	v_cvt_pk_bf16_f32 v186, v38, v39
	v_cvt_pk_bf16_f32 v187, v40, v41
	v_cvt_pk_bf16_f32 v188, v42, v43
	v_cvt_pk_bf16_f32 v189, v44, v45
	s_waitcnt lgkmcnt(5)
	v_mfma_f32_32x32x16_bf16 v[66:81], v[234:237], v[114:117], v[66:81]
	ds_read_b128 v[234:237], v243 offset:53312
	v_cvt_pk_bf16_f32 v190, v46, v47
	v_cvt_pk_bf16_f32 v191, v48, v49
	v_add_f32_e32 v172, v34, v172
	v_add_f32_e32 v173, v35, v173
	v_add_f32_e32 v176, v36, v176
	v_add_f32_e32 v179, v37, v179
	v_add_f32_e32 v172, v38, v172
	s_waitcnt lgkmcnt(5)
	v_mfma_f32_32x32x16_bf16 v[66:81], v[244:247], v[118:121], v[66:81]
	ds_read_b128 v[244:247], v243 offset:57920
	v_add_f32_e32 v173, v39, v173
	v_add_f32_e32 v176, v40, v176
	v_add_f32_e32 v179, v41, v179
	v_add_f32_e32 v172, v42, v172
	v_add_f32_e32 v173, v43, v173
	v_add_f32_e32 v176, v44, v176
	v_add_f32_e32 v179, v45, v179
	s_waitcnt lgkmcnt(5)
	v_mfma_f32_32x32x16_bf16 v[18:33], v[196:199], v[168:171], v[18:33]
	ds_read_b128 v[196:199], v243 offset:53344
	v_add_f32_e32 v172, v46, v172
	v_add_f32_e32 v173, v47, v173
	v_add_f32_e32 v176, v48, v176
	v_add_f32_e32 v179, v49, v179
	v_add_f32_e32 v172, v172, v173
	v_add_f32_e32 v176, v176, v179
	v_max3_f32 v248, v82, v83, v84
	s_waitcnt lgkmcnt(5)
	v_mfma_f32_32x32x16_bf16 v[2:17], v[200:203], v[168:171], v[2:17]
	ds_read_b128 v[200:203], v243 offset:57952
	v_max3_f32 v249, v89, v90, v91
	v_max3_f32 v248, v248, v85, v86
	v_max3_f32 v249, v249, v92, v93
	v_max3_f32 v248, v248, v87, v88
	v_max3_f32 v249, v249, v94, v95
	s_waitcnt lgkmcnt(5)
	v_mfma_f32_32x32x16_bf16 v[18:33], v[216:219], v[180:183], v[18:33]
	v_max3_f32 v250, v66, v67, v68
	v_max3_f32 v251, v73, v74, v75
	v_max3_f32 v250, v250, v69, v70
	v_max3_f32 v251, v251, v76, v77
	v_max3_f32 v250, v250, v71, v72
	v_max3_f32 v251, v251, v78, v79
	v_max3_f32 v248, v248, v249, v96
	s_waitcnt lgkmcnt(4)
	v_mfma_f32_32x32x16_bf16 v[2:17], v[230:233], v[180:183], v[2:17]
	v_max3_f32 v250, v250, v251, v80
	v_max3_f32 v248, v248, v97, v81
	v_max_f32_e32 v248, v248, v250
	v_mov_b32_e32 v249, v248
	s_waitcnt lgkmcnt(3)
	v_mfma_f32_32x32x16_bf16 v[18:33], v[234:237], v[184:187], v[18:33]
	s_waitcnt lgkmcnt(2)
	v_mfma_f32_32x32x16_bf16 v[2:17], v[244:247], v[184:187], v[2:17]
	s_waitcnt lgkmcnt(1)
	v_mfma_f32_32x32x16_bf16 v[18:33], v[196:199], v[188:191], v[18:33]
	s_waitcnt lgkmcnt(0)
	v_mfma_f32_32x32x16_bf16 v[2:17], v[200:203], v[188:191], v[2:17]
	v_add_f32_e32 v0, v172, v176
	v_add_f32_e32 v161, v161, v0
	v_permlane32_swap_b32 v248, v249
	v_max_f32_e32 v174, v248, v249
	s_setprio 0
	s_cmp_lg_u32 s32, 0
	s_cbranch_scc1 .Lfb_a1
	s_waitcnt lgkmcnt(0)
	s_barrier

; #define LAS __attribute__((address_space(3)))
; DI unsigned cvt_pk(float lo, float hi) { unsigned r; asm volatile("v_cvt_pk_bf16_f32 %0, %1, %2" : "=v"(r) : "v"(lo), "v"(hi)); return r; }
; DI float fexp2(float x) { return __builtin_amdgcn_exp2f(x); }
; template <int DK, int DV, int MODE> ...
;     ...
;   auto part2 = [&](f32x16 (&st)[2], int t) __attribute__((always_inline)) {
;     float ps0 = 0.f, ps1 = 0.f, ps2 = 0.f, ps3 = 0.f;
; #pragma unroll
;     for (int kb = 0; kb < 2; ++kb)
; #pragma unroll
;       for (int i = 0; i < 16; i += 4) {
;         const float p0 = fexp2(st[kb][i]), p1 = fexp2(st[kb][i + 1]), p2 = fexp2(st[kb][i + 2]), p3 = fexp2(st[kb][i + 3]);
;         st[kb][i] = p0; st[kb][i + 1] = p1; st[kb][i + 2] = p2; st[kb][i + 3] = p3; ps0 += p0; ps1 += p1; ps2 += p2; ps3 += p3;
;       }
;     lsum += (ps0 + ps1) + (ps2 + ps3);
;     bf16x8 pf[2][2];
; #pragma unroll
;     for (int kb = 0; kb < 2; ++kb)
; #pragma unroll
;       for (int s = 0; s < 2; ++s) { u32x4 pp; pp.x = cvt_pk(st[kb][8 * s], st[kb][8 * s + 1]); pp.y = cvt_pk(st[kb][8 * s + 2], st[kb][8 * s + 3]); pp.z = cvt_pk(st[kb][8 * s + 4], st[kb][8 * s + 5]); pp.w = cvt_pk(st[kb][8 * s + 6], st[kb][8 * s + 7]); pf[kb][s] = __builtin_bit_cast(bf16x8, pp); }
; #pragma unroll
;     for (int db = 0; db < DV / 32; ++db)
; #pragma unroll
;       for (int kb = 0; kb < 2; ++kb)
; #pragma unroll
;         for (int s = 0; s < 2; ++s) {
;           if (MODE == 1 && ((kb == 1 && s == 1 && cwu == 0) || (kb == 0 && s == 0 && cwu != 0))) continue;
;           const bf16x8 vf = *(const LAS bf16x8*)(lds + ATT_VB + (t & 3) * VBUF + (32 * db + r) * VSTR + (2 * kb + s) * 32 + hh * 16);
;           O[db] = __builtin_amdgcn_mfma_f32_32x32x16_bf16(vf, pf[kb][s], O[db], 0, 0, 0);
;         }
;   };
.Lfb_b0:
	s_and_b32 s22, s20, 2
	s_mulk_i32 s22, 0x3400
	s_mulk_i32 s21, 0x2400
	v_add_u32_e32 v252, s22, v160
	ds_read_b128 v[196:199], v252
	ds_read_b128 v[200:203], v252 offset:32
	ds_read_b128 v[216:219], v252 offset:64
	ds_read_b128 v[230:233], v252 offset:96
	ds_read_b128 v[234:237], v252 offset:128
	ds_read_b128 v[244:247], v252 offset:160
	v_add_u32_e32 v243, s21, v163
	v_add_u32_e32 v0, 0x80, v167
	v_cmp_gt_i32_e32 vcc, s78, v0
	v_exp_f32_e32 v82, v82
	v_exp_f32_e32 v83, v83
	v_cndmask_b32_e32 v34, 0, v158, vcc
	v_cmp_lt_i32_e32 vcc, s77, v0
	v_exp_f32_e32 v84, v84
	v_exp_f32_e32 v85, v85
	v_cndmask_b32_e32 v0, v34, v159, vcc
	v_cmp_neq_f32_e32 vcc, s53, v143
	v_exp_f32_e32 v86, v86
	v_exp_f32_e32 v87, v87
	v_cndmask_b32_e32 v142, 0, v143, vcc
	v_sub_f32_e32 v34, v0, v142
	v_mov_b32_e32 v35, v34
	v_mov_b32_e32 v36, v34
	v_mov_b32_e32 v37, v34
	v_mov_b32_e32 v38, v34
	v_mov_b32_e32 v39, v34
	v_mov_b32_e32 v40, v34
	v_mov_b32_e32 v41, v34
	v_mov_b32_e32 v42, v34
	v_mov_b32_e32 v43, v34
	v_mov_b32_e32 v44, v34
	v_mov_b32_e32 v45, v34
	v_mov_b32_e32 v46, v34
	v_mov_b32_e32 v47, v34
	v_mov_b32_e32 v48, v34
	v_mov_b32_e32 v49, v34
	v_exp_f32_e32 v88, v88
	v_exp_f32_e32 v89, v89
	s_waitcnt lgkmcnt(5)
	v_mfma_f32_32x32x16_bf16 v[50:65], v[196:199], v[98:101], v[34:49]
	ds_read_b128 v[196:199], v252 offset:6656
	v_exp_f32_e32 v90, v90
	v_exp_f32_e32 v91, v91
	v_exp_f32_e32 v92, v92
	v_exp_f32_e32 v93, v93
	s_waitcnt lgkmcnt(5)
	v_mfma_f32_32x32x16_bf16 v[50:65], v[200:203], v[102:105], v[50:65]
	ds_read_b128 v[200:203], v252 offset:6688
	v_exp_f32_e32 v94, v94
	v_exp_f32_e32 v95, v95
	v_exp_f32_e32 v96, v96
	v_exp_f32_e32 v97, v97
	s_waitcnt lgkmcnt(5)
	v_mfma_f32_32x32x16_bf16 v[50:65], v[216:219], v[106:109], v[50:65]
	ds_read_b128 v[216:219], v252 offset:6720
	v_exp_f32_e32 v66, v66
	v_exp_f32_e32 v67, v67
	v_cvt_pk_bf16_f32 v168, v82, v83
	v_exp_f32_e32 v68, v68
	s_waitcnt lgkmcnt(5)
	v_mfma_f32_32x32x16_bf16 v[50:65], v[230:233], v[110:113], v[50:65]
	ds_read_b128 v[230:233], v252 offset:6752
	v_exp_f32_e32 v69, v69
	v_cvt_pk_bf16_f32 v169, v84, v85
	v_exp_f32_e32 v70, v70
	v_exp_f32_e32 v71, v71
	s_waitcnt lgkmcnt(5)
	v_mfma_f32_32x32x16_bf16 v[50:65], v[234:237], v[114:117], v[50:65]
	ds_read_b128 v[234:237], v252 offset:6784
	v_cvt_pk_bf16_f32 v170, v86, v87
	v_exp_f32_e32 v72, v72
	v_exp_f32_e32 v73, v73
	v_cvt_pk_bf16_f32 v171, v88, v89
	v_exp_f32_e32 v74, v74
	s_waitcnt lgkmcnt(5)
	v_mfma_f32_32x32x16_bf16 v[50:65], v[244:247], v[118:121], v[50:65]
	ds_read_b128 v[244:247], v252 offset:6816
	v_exp_f32_e32 v75, v75
	v_cvt_pk_bf16_f32 v180, v90, v91
	v_exp_f32_e32 v76, v76
	v_exp_f32_e32 v77, v77
	s_waitcnt lgkmcnt(5)
	v_mfma_f32_32x32x16_bf16 v[34:49], v[196:199], v[98:101], v[34:49]
	ds_read_b128 v[196:199], v243 offset:53248
	v_cvt_pk_bf16_f32 v181, v92, v93
	v_exp_f32_e32 v78, v78
	v_exp_f32_e32 v79, v79
	v_cvt_pk_bf16_f32 v182, v94, v95
	v_exp_f32_e32 v80, v80
	s_waitcnt lgkmcnt(5)
	v_mfma_f32_32x32x16_bf16 v[34:49], v[200:203], v[102:105], v[34:49]
	ds_read_b128 v[200:203], v243 offset:57856
	v_exp_f32_e32 v81, v81
	v_cvt_pk_bf16_f32 v183, v96, v97
	v_add_f32_e32 v172, v82, v86
	v_add_f32_e32 v173, v83, v87
	v_add_f32_e32 v176, v84, v88
	v_add_f32_e32 v179, v85, v89
	s_waitcnt lgkmcnt(5)
	v_mfma_f32_32x32x16_bf16 v[34:49], v[216:219], v[106:109], v[34:49]
	ds_read_b128 v[216:219], v243 offset:53280
	v_add_f32_e32 v172, v90, v172
	v_add_f32_e32 v173, v91, v173
	v_add_f32_e32 v176, v92, v176
	v_add_f32_e32 v179, v93, v179
	v_add_f32_e32 v172, v94, v172
	v_add_f32_e32 v173, v95, v173
	v_add_f32_e32 v176, v96, v176
	s_waitcnt lgkmcnt(5)
	v_mfma_f32_32x32x16_bf16 v[34:49], v[230:233], v[110:113], v[34:49]
	ds_read_b128 v[230:233], v243 offset:57888
	v_add_f32_e32 v179, v97, v179
	v_cvt_pk_bf16_f32 v184, v66, v67
	v_cvt_pk_bf16_f32 v185, v68, v69
	v_cvt_pk_bf16_f32 v186, v70, v71
	v_cvt_pk_bf16_f32 v187, v72, v73
	v_cvt_pk_bf16_f32 v188, v74, v75
	v_cvt_pk_bf16_f32 v189, v76, v77
	s_waitcnt lgkmcnt(5)
	v_mfma_f32_32x32x16_bf16 v[34:49], v[234:237], v[114:117], v[34:49]
	ds_read_b128 v[234:237], v243 offset:53312
	v_cvt_pk_bf16_f32 v190, v78, v79
	v_cvt_pk_bf16_f32 v191, v80, v81
	v_add_f32_e32 v172, v66, v172
	v_add_f32_e32 v173, v67, v173
	v_add_f32_e32 v176, v68, v176
	v_add_f32_e32 v179, v69, v179
	v_add_f32_e32 v172, v70, v172
	s_waitcnt lgkmcnt(5)
	v_mfma_f32_32x32x16_bf16 v[34:49], v[244:247], v[118:121], v[34:49]
	ds_read_b128 v[244:247], v243 offset:57920
	v_add_f32_e32 v173, v71, v173
	v_add_f32_e32 v176, v72, v176
	v_add_f32_e32 v179, v73, v179
	v_add_f32_e32 v172, v74, v172
	v_add_f32_e32 v173, v75, v173
	v_add_f32_e32 v176, v76, v176
	v_add_f32_e32 v179, v77, v179
	s_waitcnt lgkmcnt(5)
	v_mfma_f32_32x32x16_bf16 v[18:33], v[196:199], v[168:171], v[18:33]
	ds_read_b128 v[196:199], v243 offset:53344
	v_add_f32_e32 v172, v78, v172
	v_add_f32_e32 v173, v79, v173
	v_add_f32_e32 v176, v80, v176
	v_add_f32_e32 v179, v81, v179
	v_add_f32_e32 v172, v172, v173
	v_add_f32_e32 v176, v176, v179
	v_max3_f32 v248, v50, v51, v52
	s_waitcnt lgkmcnt(5)
	v_mfma_f32_32x32x16_bf16 v[2:17], v[200:203], v[168:171], v[2:17]
	ds_read_b128 v[200:203], v243 offset:57952
	v_max3_f32 v249, v57, v58, v59
	v_max3_f32 v248, v248, v53, v54
	v_max3_f32 v249, v249, v60, v61
	v_max3_f32 v248, v248, v55, v56
	v_max3_f32 v249, v249, v62, v63
	s_waitcnt lgkmcnt(5)
	v_mfma_f32_32x32x16_bf16 v[18:33], v[216:219], v[180:183], v[18:33]
	v_max3_f32 v250, v34, v35, v36
	v_max3_f32 v251, v41, v42, v43
	v_max3_f32 v250, v250, v37, v38
	v_max3_f32 v251, v251, v44, v45
	v_max3_f32 v250, v250, v39, v40
	v_max3_f32 v251, v251, v46, v47
	v_max3_f32 v248, v248, v249, v64
	s_waitcnt lgkmcnt(4)
	v_mfma_f32_32x32x16_bf16 v[2:17], v[230:233], v[180:183], v[2:17]
	v_max3_f32 v250, v250, v251, v48
	v_max3_f32 v248, v248, v65, v49
	v_max_f32_e32 v248, v248, v250
	v_mov_b32_e32 v249, v248
	s_waitcnt lgkmcnt(3)
	v_mfma_f32_32x32x16_bf16 v[18:33], v[234:237], v[184:187], v[18:33]
	s_waitcnt lgkmcnt(2)
	v_mfma_f32_32x32x16_bf16 v[2:17], v[244:247], v[184:187], v[2:17]
	s_waitcnt lgkmcnt(1)
	v_mfma_f32_32x32x16_bf16 v[18:33], v[196:199], v[188:191], v[18:33]
	s_waitcnt lgkmcnt(0)
	v_mfma_f32_32x32x16_bf16 v[2:17], v[200:203], v[188:191], v[2:17]
	v_add_f32_e32 v0, v172, v176
	v_add_f32_e32 v161, v161, v0
	v_permlane32_swap_b32 v248, v249
	v_max_f32_e32 v174, v248, v249
	s_setprio 0
	s_cmp_lg_u32 s32, 0
	s_cbranch_scc1 .Lfb_b1
	s_waitcnt lgkmcnt(0)
	s_barrier
